# P4 tile order: the token-tile index inside each 4x22 group rotated by (pn>>3) so that boundary tiles spread over the workgroups (max 5 instead of 13 per workgroup)
# speedup vs baseline: 1.0134x; 1.0042x over previous
;     __host__ __device__ bool next(int i, Unit& u) const {
;     ...
;         int wgid = (int)L; { const int q = nwg / NXCD, r = nwg % NXCD, xcd = wgid % NXCD, off = wgid / NXCD; wgid = (xcd < r ? xcd * (q + 1) : r * (q + 1) + (xcd - r) * q) + off; }
;         const int nig = WGM * nN, gid = wgid / nig, fm = gid * WGM, gsz = (nM - fm) < WGM ? (nM - fm) : WGM;
;         u.pm = fm + ((wgid % nig) % gsz); u.pn = (wgid % nig) / gsz; return true;
.LBB0_549:
	s_ashr_i32 s2, s5, 3
	s_add_i32 s2, s7, s2
	s_mul_hi_i32 s3, s2, 0x2e8ba2e9
	s_lshr_b32 s5, s3, 31
	s_ashr_i32 s3, s3, 4
	s_add_i32 s3, s3, s5
	s_lshl_b32 s5, s3, 2
	s_sub_i32 s6, 0x205, s5
	s_mulk_i32 s3, 0x58
	s_min_u32 s6, s6, 4
	s_sub_i32 s7, s2, s3
	s_sext_i32_i8 s2, s7
	v_cvt_f32_ubyte0_e32 v2, s6
	v_cvt_f32_i32_e32 v1, s2
	v_rcp_iflag_f32_e32 v3, v2
	s_ashr_i32 s2, s2, 30
	s_or_b32 s8, s2, 1
	v_mul_f32_e32 v3, v1, v3
	v_trunc_f32_e32 v3, v3
	v_fma_f32 v1, -v3, v2, v1
	v_cvt_i32_f32_e32 v3, v3
	v_cmp_ge_f32_e64 s[2:3], |v1|, v2
	s_and_b64 s[2:3], s[2:3], exec
	s_cselect_b32 s2, s8, 0
	v_readfirstlane_b32 s3, v3
	s_add_i32 s2, s3, s2
	s_sext_i32_i8 s10, s2
	s_mul_i32 s2, s2, s6
	s_sub_i32 s2, s7, s2
	s_sext_i32_i8 s2, s2
	s_lshr_b32 s3, s10, 3
	s_add_i32 s2, s2, s3
	s_add_i32 s3, s6, -1
	s_and_b32 s2, s2, s3
	s_add_i32 s12, s5, s2

;     __host__ __device__ bool next(int i, Unit& u) const {
;     ...
;         int wgid = (int)L; { const int q = nwg / NXCD, r = nwg % NXCD, xcd = wgid % NXCD, off = wgid / NXCD; wgid = (xcd < r ? xcd * (q + 1) : r * (q + 1) + (xcd - r) * q) + off; }
;         const int nig = WGM * nN, gid = wgid / nig, fm = gid * WGM, gsz = (nM - fm) < WGM ? (nM - fm) : WGM;
;         u.pm = fm + ((wgid % nig) % gsz); u.pn = (wgid % nig) / gsz; return true;
.LBB0_561:
	s_ashr_i32 s4, s11, 3
	s_add_i32 s4, s14, s4
	s_mul_hi_i32 s5, s4, 0x2e8ba2e9
	s_lshr_b32 s11, s5, 31
	s_ashr_i32 s5, s5, 4
	s_add_i32 s5, s5, s11
	s_lshl_b32 s11, s5, 2
	s_sub_i32 s13, 0x205, s11
	s_min_i32 s13, s13, 4
	s_abs_i32 s14, s13
	v_cvt_f32_u32_e32 v0, s14
	s_sub_i32 s16, 0, s14
	s_mulk_i32 s5, 0x58
	s_sub_i32 s4, s4, s5
	v_rcp_iflag_f32_e32 v0, v0
	s_abs_i32 s5, s4
	s_xor_b32 s15, s4, s13
	s_ashr_i32 s15, s15, 31
	v_mul_f32_e32 v0, 0x4f7ffffe, v0
	v_cvt_u32_f32_e32 v0, v0
	s_nop 0
	v_readfirstlane_b32 s17, v0
	s_mul_i32 s16, s16, s17
	s_mul_hi_u32 s16, s17, s16
	s_add_i32 s17, s17, s16
	s_mul_hi_u32 s16, s5, s17
	s_mul_i32 s17, s16, s14
	s_sub_i32 s5, s5, s17
	s_add_i32 s18, s16, 1
	s_sub_i32 s17, s5, s14
	s_cmp_ge_u32 s5, s14
	s_cselect_b32 s16, s18, s16
	s_cselect_b32 s5, s17, s5
	s_add_i32 s17, s16, 1
	s_cmp_ge_u32 s5, s14
	s_cselect_b32 s5, s17, s16
	s_xor_b32 s5, s5, s15
	s_sub_i32 s92, s5, s15
	s_mul_i32 s5, s92, s13
	s_sub_i32 s4, s4, s5
	s_lshr_b32 s5, s92, 3
	s_add_i32 s4, s4, s5
	s_add_i32 s5, s13, -1
	s_and_b32 s4, s4, s5
	s_add_i32 s4, s11, s4
	v_writelane_b32 v255, s4, 44
